# speedup vs baseline: 1.0113x; 1.0113x over previous
.Lxb_not1:
	s_cmp_lg_u32 s9, 2
	s_cbranch_scc1 .Lxb_ge3
	v_readlane_b32 s12, v255, 9
	s_nop 0
	s_lshr_b32 s12, s12, 6
	v_mov_b32_e32 v1, s12
	global_load_dword v1, v1, s[2:3] offset:2368 sc1
	s_waitcnt vmcnt(0)
	v_readfirstlane_b32 s8, v1
	s_nop 0
	s_bcnt1_i32_b32 s8, s8
	s_cmp_eq_u32 s8, 1
	s_cselect_b32 s100, 1, 2
	s_cbranch_scc1 .Lxb_arrive
	s_branch .Lxb_cons

.LBB0_2681:
	s_or_b64 exec, exec, s[8:9]
	v_readlane_b32 s8, v255, 13
	v_readlane_b32 s6, v255, 6
	v_readlane_b32 s9, v255, 14
	s_add_i32 s6, s8, s6
	v_readlane_b32 s8, v255, 2
	v_readlane_b32 s7, v255, 17
	s_lshr_b32 s6, s6, 3
	s_sub_i32 s11, s7, s8
	s_waitcnt vmcnt(0)
	v_readfirstlane_b32 s7, v1
	s_mul_i32 s6, s6, s11
	v_readlane_b32 s9, v255, 3
	v_add3_u32 v0, s7, v0, 1
	v_cmp_eq_u32_e32 vcc, s6, v0
	s_and_saveexec_b64 s[6:7], vcc
	s_cbranch_execz .LBB0_2684
	s_mov_b64 s[8:9], exec
	v_mbcnt_lo_u32_b32 v0, s8, 0
	v_mbcnt_hi_u32_b32 v0, s9, v0
	v_cmp_eq_u32_e32 vcc, 0, v0
	s_and_b64 s[12:13], exec, vcc
	s_mov_b64 exec, s[12:13]
	s_cbranch_execz .LBB0_2684
	s_bcnt1_i32_b64 s8, s[8:9]
	v_mov_b32_e32 v0, s8
	s_cmp_eq_u32 s100, 1
	s_cbranch_scc0 .Lxb_top
	s_bitcmp1_b32 0x20402040, s11
	s_cbranch_scc1 .Lxb_top
	buffer_wbl2 sc1
	s_waitcnt vmcnt(0)
